# P4 post-carry prefix over predecessor slots rewritten with DPP-fused v_fmac/v_mul (same operations, fewer VALU instructions)
# baseline (speedup 1.0000x reference)
.LBB0_534:
	s_or_b64 exec, exec, s[8:9]
	v_lshlrev_b32_e32 v0, 4, v237
	v_and_b32_e32 v0, 48, v0
	v_and_or_b32 v0, v227, 64, v0
	v_lshlrev_b32_e32 v0, 2, v0
	v_fmac_f32_dpp v31, v31, v30 row_shr:1 row_mask:0xf bank_mask:0xf
	v_fmac_f32_dpp v29, v29, v28 row_shr:1 row_mask:0xf bank_mask:0xf
	v_fmac_f32_dpp v27, v27, v26 row_shr:1 row_mask:0xf bank_mask:0xf
	v_fmac_f32_dpp v25, v25, v24 row_shr:1 row_mask:0xf bank_mask:0xf
	v_fmac_f32_dpp v23, v23, v22 row_shr:1 row_mask:0xf bank_mask:0xf
	v_fmac_f32_dpp v21, v21, v20 row_shr:1 row_mask:0xf bank_mask:0xf
	v_fmac_f32_dpp v19, v19, v18 row_shr:1 row_mask:0xf bank_mask:0xf
	v_fmac_f32_dpp v17, v17, v16 row_shr:1 row_mask:0xf bank_mask:0xf
	v_mul_f32_dpp v30, v30, v30 row_shr:1 row_mask:0xf bank_mask:0xf
	v_mul_f32_dpp v28, v28, v28 row_shr:1 row_mask:0xf bank_mask:0xf
	v_mul_f32_dpp v26, v26, v26 row_shr:1 row_mask:0xf bank_mask:0xf
	v_mul_f32_dpp v24, v24, v24 row_shr:1 row_mask:0xf bank_mask:0xf
	v_mul_f32_dpp v22, v22, v22 row_shr:1 row_mask:0xf bank_mask:0xf
	v_mul_f32_dpp v20, v20, v20 row_shr:1 row_mask:0xf bank_mask:0xf
	v_mul_f32_dpp v18, v18, v18 row_shr:1 row_mask:0xf bank_mask:0xf
	v_mul_f32_dpp v16, v16, v16 row_shr:1 row_mask:0xf bank_mask:0xf
	v_fmac_f32_dpp v31, v31, v30 row_shr:2 row_mask:0xf bank_mask:0xf
	v_fmac_f32_dpp v29, v29, v28 row_shr:2 row_mask:0xf bank_mask:0xf
	v_fmac_f32_dpp v27, v27, v26 row_shr:2 row_mask:0xf bank_mask:0xf
	v_fmac_f32_dpp v25, v25, v24 row_shr:2 row_mask:0xf bank_mask:0xf
	v_fmac_f32_dpp v23, v23, v22 row_shr:2 row_mask:0xf bank_mask:0xf
	v_fmac_f32_dpp v21, v21, v20 row_shr:2 row_mask:0xf bank_mask:0xf
	v_fmac_f32_dpp v19, v19, v18 row_shr:2 row_mask:0xf bank_mask:0xf
	v_fmac_f32_dpp v17, v17, v16 row_shr:2 row_mask:0xf bank_mask:0xf
	v_mul_f32_dpp v30, v30, v30 row_shr:2 row_mask:0xf bank_mask:0xf
	v_mul_f32_dpp v28, v28, v28 row_shr:2 row_mask:0xf bank_mask:0xf
	v_mul_f32_dpp v26, v26, v26 row_shr:2 row_mask:0xf bank_mask:0xf
	v_mul_f32_dpp v24, v24, v24 row_shr:2 row_mask:0xf bank_mask:0xf
	v_mul_f32_dpp v22, v22, v22 row_shr:2 row_mask:0xf bank_mask:0xf
	v_mul_f32_dpp v20, v20, v20 row_shr:2 row_mask:0xf bank_mask:0xf
	v_mul_f32_dpp v18, v18, v18 row_shr:2 row_mask:0xf bank_mask:0xf
	v_mul_f32_dpp v16, v16, v16 row_shr:2 row_mask:0xf bank_mask:0xf
	v_fmac_f32_dpp v31, v31, v30 row_shr:4 row_mask:0xf bank_mask:0xf
	v_fmac_f32_dpp v29, v29, v28 row_shr:4 row_mask:0xf bank_mask:0xf
	v_fmac_f32_dpp v27, v27, v26 row_shr:4 row_mask:0xf bank_mask:0xf
	v_fmac_f32_dpp v25, v25, v24 row_shr:4 row_mask:0xf bank_mask:0xf
	v_fmac_f32_dpp v23, v23, v22 row_shr:4 row_mask:0xf bank_mask:0xf
	v_fmac_f32_dpp v21, v21, v20 row_shr:4 row_mask:0xf bank_mask:0xf
	v_fmac_f32_dpp v19, v19, v18 row_shr:4 row_mask:0xf bank_mask:0xf
	v_fmac_f32_dpp v17, v17, v16 row_shr:4 row_mask:0xf bank_mask:0xf
	v_mul_f32_dpp v30, v30, v30 row_shr:4 row_mask:0xf bank_mask:0xf
	v_mul_f32_dpp v28, v28, v28 row_shr:4 row_mask:0xf bank_mask:0xf
	v_mul_f32_dpp v26, v26, v26 row_shr:4 row_mask:0xf bank_mask:0xf
	v_mul_f32_dpp v24, v24, v24 row_shr:4 row_mask:0xf bank_mask:0xf
	v_mul_f32_dpp v22, v22, v22 row_shr:4 row_mask:0xf bank_mask:0xf
	v_mul_f32_dpp v20, v20, v20 row_shr:4 row_mask:0xf bank_mask:0xf
	v_mul_f32_dpp v18, v18, v18 row_shr:4 row_mask:0xf bank_mask:0xf
	v_mul_f32_dpp v16, v16, v16 row_shr:4 row_mask:0xf bank_mask:0xf
	v_fmac_f32_dpp v31, v31, v30 row_shr:8 row_mask:0xf bank_mask:0xf
	v_fmac_f32_dpp v29, v29, v28 row_shr:8 row_mask:0xf bank_mask:0xf
	v_fmac_f32_dpp v27, v27, v26 row_shr:8 row_mask:0xf bank_mask:0xf
	v_fmac_f32_dpp v25, v25, v24 row_shr:8 row_mask:0xf bank_mask:0xf
	v_fmac_f32_dpp v23, v23, v22 row_shr:8 row_mask:0xf bank_mask:0xf
	v_fmac_f32_dpp v21, v21, v20 row_shr:8 row_mask:0xf bank_mask:0xf
	v_fmac_f32_dpp v19, v19, v18 row_shr:8 row_mask:0xf bank_mask:0xf
	v_fmac_f32_dpp v17, v17, v16 row_shr:8 row_mask:0xf bank_mask:0xf
	ds_bpermute_b32 v2, v0, v31 offset:60
	ds_bpermute_b32 v4, v0, v29 offset:60
	ds_bpermute_b32 v6, v0, v27 offset:60
	ds_bpermute_b32 v8, v0, v25 offset:60
	s_waitcnt lgkmcnt(3)
	v_fmac_f32_e32 v92, v15, v2
	s_waitcnt lgkmcnt(2)
	v_fmac_f32_e32 v94, v13, v4
	s_waitcnt lgkmcnt(1)
	v_fmac_f32_e32 v148, v11, v6
	s_waitcnt lgkmcnt(0)
	v_fmac_f32_e32 v150, v9, v8
	ds_bpermute_b32 v2, v0, v23 offset:60
	ds_bpermute_b32 v4, v0, v21 offset:60
	ds_bpermute_b32 v6, v0, v19 offset:60
	ds_bpermute_b32 v0, v0, v17 offset:60
	s_waitcnt lgkmcnt(3)
	v_fmac_f32_e32 v152, v5, v2
	s_waitcnt lgkmcnt(2)
	v_fmac_f32_e32 v154, v3, v4
	s_waitcnt lgkmcnt(1)
	v_fmac_f32_e32 v200, v1, v6
	s_waitcnt lgkmcnt(0)
	v_fmac_f32_e32 v202, v7, v0
	v_lshl_add_u64 v[0:1], s[38:39], 0, v[164:165]
	global_load_dwordx4 v[204:207], v[0:1], off
	v_lshl_add_u64 v[0:1], s[40:41], 0, v[164:165]
	global_load_dwordx4 v[208:211], v[0:1], off
	v_lshl_add_u64 v[0:1], s[38:39], 0, v[182:183]
	global_load_dwordx4 v[212:215], v[0:1], off
	v_lshl_add_u64 v[0:1], s[40:41], 0, v[182:183]
	global_load_dwordx4 v[216:219], v[0:1], off
	v_lshl_add_u64 v[0:1], s[38:39], 0, v[180:181]
	global_load_dwordx4 v[220:223], v[0:1], off
	v_lshl_add_u64 v[0:1], s[40:41], 0, v[180:181]
	global_load_dwordx4 v[238:241], v[0:1], off
	v_lshl_add_u64 v[0:1], s[38:39], 0, v[178:179]
	global_load_dwordx4 v[242:245], v[0:1], off
	v_lshl_add_u64 v[0:1], s[40:41], 0, v[178:179]
	global_load_dwordx4 v[246:249], v[0:1], off
	v_add_u32_e32 v0, 0x2000, v232
	v_add_u32_e32 v1, v0, v233
	global_load_dwordx4 v[24:27], v1, s[38:39]
	global_load_dwordx4 v[28:31], v1, s[40:41]
	v_add_u32_e32 v1, v234, v0
	global_load_dwordx4 v[16:19], v1, s[38:39]
	global_load_dwordx4 v[20:23], v1, s[40:41]
	v_add_u32_e32 v1, v235, v0
	v_add_u32_e32 v4, v236, v0
	global_load_dwordx4 v[8:11], v1, s[38:39]
	global_load_dwordx4 v[12:15], v1, s[40:41]
	s_nop 0
	global_load_dwordx4 v[0:3], v4, s[38:39]
	s_nop 0
	global_load_dwordx4 v[4:7], v4, s[40:41]
	v_fmac_f32_e32 v184, v136, v92
	s_waitcnt vmcnt(15)
	v_lshlrev_b32_e32 v93, 16, v204
	s_waitcnt vmcnt(14)
	v_lshlrev_b32_e32 v95, 16, v208
	v_fmac_f32_e32 v186, v128, v94
	v_fmac_f32_e32 v93, v184, v95
	v_and_b32_e32 v95, 0xffff0000, v204
	v_and_b32_e32 v128, 0xffff0000, v208
	v_fmac_f32_e32 v95, v186, v128
	v_cvt_pk_bf16_f32 v204, v93, v95
	v_fmac_f32_e32 v188, v138, v148
	v_lshlrev_b32_e32 v93, 16, v205
	v_lshlrev_b32_e32 v95, 16, v209
	v_fmac_f32_e32 v190, v130, v150
	v_fmac_f32_e32 v93, v188, v95
	v_and_b32_e32 v95, 0xffff0000, v205
	v_and_b32_e32 v128, 0xffff0000, v209
	v_fmac_f32_e32 v95, v190, v128
	v_cvt_pk_bf16_f32 v205, v93, v95
	v_fmac_f32_e32 v192, v124, v152
	v_lshlrev_b32_e32 v93, 16, v206
	v_lshlrev_b32_e32 v95, 16, v210
	v_fmac_f32_e32 v194, v120, v154
	v_fmac_f32_e32 v93, v192, v95
	v_and_b32_e32 v95, 0xffff0000, v206
	v_and_b32_e32 v120, 0xffff0000, v210
	v_fmac_f32_e32 v95, v194, v120
	v_cvt_pk_bf16_f32 v206, v93, v95
	v_fmac_f32_e32 v196, v122, v200
	v_lshlrev_b32_e32 v93, 16, v207
	v_lshlrev_b32_e32 v95, 16, v211
	v_fmac_f32_e32 v198, v126, v202
	v_fmac_f32_e32 v93, v196, v95
	v_and_b32_e32 v95, 0xffff0000, v207
	v_and_b32_e32 v120, 0xffff0000, v211
	v_fmac_f32_e32 v95, v198, v120
	v_cvt_pk_bf16_f32 v207, v93, v95
	v_fmac_f32_e32 v108, v109, v92
	s_waitcnt vmcnt(13)
	v_lshlrev_b32_e32 v93, 16, v212
	s_waitcnt vmcnt(12)
	v_lshlrev_b32_e32 v95, 16, v216
	v_fmac_f32_e32 v116, v117, v94
	v_fmac_f32_e32 v93, v108, v95
	v_and_b32_e32 v95, 0xffff0000, v212
	v_and_b32_e32 v108, 0xffff0000, v216
	v_lshl_add_u64 v[208:209], s[28:29], 0, v[164:165]
	v_fmac_f32_e32 v95, v116, v108
	global_store_dwordx4 v[208:209], v[204:207], off
	v_cvt_pk_bf16_f32 v108, v93, v95
	v_fmac_f32_e32 v110, v111, v148
	v_lshlrev_b32_e32 v93, 16, v213
	v_lshlrev_b32_e32 v95, 16, v217
	v_fmac_f32_e32 v118, v119, v150
	v_fmac_f32_e32 v93, v110, v95
	v_and_b32_e32 v95, 0xffff0000, v213
	v_and_b32_e32 v109, 0xffff0000, v217
	v_fmac_f32_e32 v95, v118, v109
	v_cvt_pk_bf16_f32 v109, v93, v95
	v_fmac_f32_e32 v100, v101, v152
	v_lshlrev_b32_e32 v93, 16, v214
	v_lshlrev_b32_e32 v95, 16, v218
	v_fmac_f32_e32 v104, v105, v154
	v_fmac_f32_e32 v93, v100, v95
	v_and_b32_e32 v95, 0xffff0000, v214
	v_and_b32_e32 v100, 0xffff0000, v218
	v_fmac_f32_e32 v95, v104, v100
	v_cvt_pk_bf16_f32 v110, v93, v95
	v_fmac_f32_e32 v102, v103, v200
	v_lshlrev_b32_e32 v93, 16, v215
	v_lshlrev_b32_e32 v95, 16, v219
	v_fmac_f32_e32 v106, v107, v202
	v_fmac_f32_e32 v93, v102, v95
	v_and_b32_e32 v95, 0xffff0000, v215
	v_and_b32_e32 v100, 0xffff0000, v219
	v_fmac_f32_e32 v95, v106, v100
	v_cvt_pk_bf16_f32 v111, v93, v95
	v_fmac_f32_e32 v88, v89, v92
	s_waitcnt vmcnt(12)
	v_lshlrev_b32_e32 v89, 16, v220
	s_waitcnt vmcnt(11)
	v_lshlrev_b32_e32 v93, 16, v238
	v_fmac_f32_e32 v96, v97, v94
	v_fmac_f32_e32 v89, v88, v93
	v_and_b32_e32 v88, 0xffff0000, v220
	v_and_b32_e32 v93, 0xffff0000, v238
	v_lshl_add_u64 v[100:101], s[28:29], 0, v[182:183]
	v_fmac_f32_e32 v88, v96, v93
	global_store_dwordx4 v[100:101], v[108:111], off
	v_cvt_pk_bf16_f32 v88, v89, v88
	v_fmac_f32_e32 v90, v91, v148
	v_lshlrev_b32_e32 v89, 16, v221
	v_lshlrev_b32_e32 v91, 16, v239
	v_fmac_f32_e32 v80, v81, v152
	v_fmac_f32_e32 v84, v85, v154
	v_lshlrev_b32_e32 v81, 16, v222
	v_lshlrev_b32_e32 v85, 16, v240
	v_fmac_f32_e32 v98, v99, v150
	v_fmac_f32_e32 v89, v90, v91
	v_and_b32_e32 v90, 0xffff0000, v221
	v_and_b32_e32 v91, 0xffff0000, v239
	v_fmac_f32_e32 v81, v80, v85
	v_and_b32_e32 v80, 0xffff0000, v222
	v_and_b32_e32 v85, 0xffff0000, v240
	v_fmac_f32_e32 v90, v98, v91
	v_fmac_f32_e32 v80, v84, v85
	v_cvt_pk_bf16_f32 v89, v89, v90
	v_cvt_pk_bf16_f32 v90, v81, v80
	v_fmac_f32_e32 v82, v83, v200
	v_lshlrev_b32_e32 v80, 16, v223
	v_lshlrev_b32_e32 v81, 16, v241
	v_fmac_f32_e32 v86, v87, v202
	v_fmac_f32_e32 v80, v82, v81
	v_and_b32_e32 v81, 0xffff0000, v223
	v_and_b32_e32 v82, 0xffff0000, v241
	v_fmac_f32_e32 v72, v73, v92
	v_fmac_f32_e32 v76, v77, v94
	s_waitcnt vmcnt(11)
	v_lshlrev_b32_e32 v73, 16, v242
	s_waitcnt vmcnt(10)
	v_lshlrev_b32_e32 v77, 16, v246
	v_fmac_f32_e32 v81, v86, v82
	v_fmac_f32_e32 v73, v72, v77
	v_and_b32_e32 v72, 0xffff0000, v242
	v_and_b32_e32 v77, 0xffff0000, v246
	v_cvt_pk_bf16_f32 v91, v80, v81
	v_lshl_add_u64 v[80:81], s[28:29], 0, v[180:181]
	v_fmac_f32_e32 v72, v76, v77
	global_store_dwordx4 v[80:81], v[88:91], off
	v_cvt_pk_bf16_f32 v72, v73, v72
	v_fmac_f32_e32 v74, v75, v148
	v_lshlrev_b32_e32 v73, 16, v243
	v_lshlrev_b32_e32 v75, 16, v247
	v_fmac_f32_e32 v64, v65, v152
	v_fmac_f32_e32 v68, v69, v154
	v_lshlrev_b32_e32 v65, 16, v244
	v_lshlrev_b32_e32 v69, 16, v248
	v_fmac_f32_e32 v78, v79, v150
	v_fmac_f32_e32 v73, v74, v75
	v_and_b32_e32 v74, 0xffff0000, v243
	v_and_b32_e32 v75, 0xffff0000, v247
	v_fmac_f32_e32 v65, v64, v69
	v_and_b32_e32 v64, 0xffff0000, v244
	v_and_b32_e32 v69, 0xffff0000, v248
	v_fmac_f32_e32 v74, v78, v75
	v_fmac_f32_e32 v64, v68, v69
	v_cvt_pk_bf16_f32 v73, v73, v74
	v_cvt_pk_bf16_f32 v74, v65, v64
	v_fmac_f32_e32 v66, v67, v200
	v_lshlrev_b32_e32 v64, 16, v245
	v_lshlrev_b32_e32 v65, 16, v249
	v_fmac_f32_e32 v70, v71, v202
	v_fmac_f32_e32 v64, v66, v65
	v_and_b32_e32 v65, 0xffff0000, v245
	v_and_b32_e32 v66, 0xffff0000, v249
	v_fmac_f32_e32 v65, v70, v66
	v_cvt_pk_bf16_f32 v75, v64, v65
	v_lshl_add_u64 v[64:65], s[28:29], 0, v[178:179]
	global_store_dwordx4 v[64:65], v[72:75], off
	v_fmac_f32_e32 v56, v57, v92
	v_fmac_f32_e32 v60, v61, v94
	s_waitcnt vmcnt(11)
	v_lshlrev_b32_e32 v57, 16, v24
	s_waitcnt vmcnt(10)
	v_lshlrev_b32_e32 v61, 16, v28
	v_and_b32_e32 v24, 0xffff0000, v24
	v_and_b32_e32 v28, 0xffff0000, v28
	v_fmac_f32_e32 v57, v56, v61
	v_fmac_f32_e32 v24, v60, v28
	v_fmac_f32_e32 v58, v59, v148
	v_fmac_f32_e32 v62, v63, v150
	v_lshlrev_b32_e32 v28, 16, v25
	v_lshlrev_b32_e32 v56, 16, v29
	v_and_b32_e32 v25, 0xffff0000, v25
	v_and_b32_e32 v29, 0xffff0000, v29
	v_fmac_f32_e32 v28, v58, v56
	v_fmac_f32_e32 v25, v62, v29
	v_cvt_pk_bf16_f32 v24, v57, v24
	v_cvt_pk_bf16_f32 v25, v28, v25
	v_fmac_f32_e32 v48, v49, v152
	v_lshlrev_b32_e32 v28, 16, v26
	v_lshlrev_b32_e32 v29, 16, v30
	v_fmac_f32_e32 v52, v53, v154
	v_fmac_f32_e32 v28, v48, v29
	v_and_b32_e32 v26, 0xffff0000, v26
	v_and_b32_e32 v29, 0xffff0000, v30
	v_fmac_f32_e32 v26, v52, v29
	v_cvt_pk_bf16_f32 v26, v28, v26
	v_fmac_f32_e32 v50, v51, v200
	v_lshlrev_b32_e32 v28, 16, v27
	v_lshlrev_b32_e32 v29, 16, v31
	v_fmac_f32_e32 v54, v55, v202
	v_fmac_f32_e32 v28, v50, v29
	v_and_b32_e32 v27, 0xffff0000, v27
	v_and_b32_e32 v29, 0xffff0000, v31
	v_fmac_f32_e32 v27, v54, v29
	v_cvt_pk_bf16_f32 v27, v28, v27
	v_lshl_add_u64 v[28:29], s[28:29], 0, v[176:177]
	global_store_dwordx4 v[28:29], v[24:27], off
	v_fmac_f32_e32 v40, v41, v92
	v_fmac_f32_e32 v44, v45, v94
	s_waitcnt vmcnt(10)
	v_lshlrev_b32_e32 v24, 16, v16
	s_waitcnt vmcnt(9)
	v_lshlrev_b32_e32 v25, 16, v20
	v_and_b32_e32 v16, 0xffff0000, v16
	v_and_b32_e32 v20, 0xffff0000, v20
	v_fmac_f32_e32 v24, v40, v25
	v_fmac_f32_e32 v16, v44, v20
	v_cvt_pk_bf16_f32 v16, v24, v16
	v_fmac_f32_e32 v42, v43, v148
	v_fmac_f32_e32 v46, v47, v150
	v_lshlrev_b32_e32 v20, 16, v17
	v_lshlrev_b32_e32 v24, 16, v21
	v_and_b32_e32 v17, 0xffff0000, v17
	v_and_b32_e32 v21, 0xffff0000, v21
	v_fmac_f32_e32 v20, v42, v24
	v_fmac_f32_e32 v17, v46, v21
	v_cvt_pk_bf16_f32 v17, v20, v17
	v_fmac_f32_e32 v32, v33, v152
	v_lshlrev_b32_e32 v20, 16, v18
	v_lshlrev_b32_e32 v21, 16, v22
	v_fmac_f32_e32 v36, v37, v154
	v_fmac_f32_e32 v20, v32, v21
	v_and_b32_e32 v18, 0xffff0000, v18
	v_and_b32_e32 v21, 0xffff0000, v22
	v_fmac_f32_e32 v18, v36, v21
	v_cvt_pk_bf16_f32 v18, v20, v18
	v_fmac_f32_e32 v34, v35, v200
	v_lshlrev_b32_e32 v20, 16, v19
	v_lshlrev_b32_e32 v21, 16, v23
	v_fmac_f32_e32 v38, v39, v202
	v_fmac_f32_e32 v20, v34, v21
	v_and_b32_e32 v19, 0xffff0000, v19
	v_and_b32_e32 v21, 0xffff0000, v23
	v_fmac_f32_e32 v19, v38, v21
	v_cvt_pk_bf16_f32 v19, v20, v19
	v_lshl_add_u64 v[20:21], s[28:29], 0, v[174:175]
	global_store_dwordx4 v[20:21], v[16:19], off
	v_fmac_f32_e32 v112, v113, v92
	v_fmac_f32_e32 v114, v115, v94
	s_waitcnt vmcnt(9)
	v_lshlrev_b32_e32 v16, 16, v8
	s_waitcnt vmcnt(8)
	v_lshlrev_b32_e32 v17, 16, v12
	v_and_b32_e32 v8, 0xffff0000, v8
	v_and_b32_e32 v12, 0xffff0000, v12
	v_fmac_f32_e32 v16, v112, v17
	v_fmac_f32_e32 v8, v114, v12
	v_cvt_pk_bf16_f32 v8, v16, v8
	v_fmac_f32_e32 v132, v121, v148
	v_fmac_f32_e32 v134, v123, v150
	v_lshlrev_b32_e32 v12, 16, v9
	v_lshlrev_b32_e32 v16, 16, v13
	v_and_b32_e32 v9, 0xffff0000, v9
	v_and_b32_e32 v13, 0xffff0000, v13
	v_fmac_f32_e32 v12, v132, v16
	v_fmac_f32_e32 v9, v134, v13
	v_cvt_pk_bf16_f32 v9, v12, v9
	v_fmac_f32_e32 v140, v125, v152
	v_lshlrev_b32_e32 v12, 16, v10
	v_lshlrev_b32_e32 v13, 16, v14
	v_fmac_f32_e32 v142, v127, v154
	v_fmac_f32_e32 v12, v140, v13
	v_and_b32_e32 v10, 0xffff0000, v10
	v_and_b32_e32 v13, 0xffff0000, v14
	v_fmac_f32_e32 v10, v142, v13
	v_cvt_pk_bf16_f32 v10, v12, v10
	v_fmac_f32_e32 v144, v129, v200
	v_lshlrev_b32_e32 v12, 16, v11
	v_lshlrev_b32_e32 v13, 16, v15
	v_fmac_f32_e32 v146, v131, v202
	v_fmac_f32_e32 v12, v144, v13
	v_and_b32_e32 v11, 0xffff0000, v11
	v_and_b32_e32 v13, 0xffff0000, v15
	v_fmac_f32_e32 v11, v146, v13
	v_cvt_pk_bf16_f32 v11, v12, v11
	v_lshl_add_u64 v[12:13], s[28:29], 0, v[172:173]
	global_store_dwordx4 v[12:13], v[8:11], off
	v_fmac_f32_e32 v133, v135, v92
	v_fmac_f32_e32 v137, v141, v94
	s_waitcnt vmcnt(8)
	v_lshlrev_b32_e32 v8, 16, v0
	s_waitcnt vmcnt(7)
	v_lshlrev_b32_e32 v9, 16, v4
	v_and_b32_e32 v0, 0xffff0000, v0
	v_and_b32_e32 v4, 0xffff0000, v4
	v_fmac_f32_e32 v8, v133, v9
	v_fmac_f32_e32 v0, v137, v4
	v_cvt_pk_bf16_f32 v0, v8, v0
	v_fmac_f32_e32 v139, v143, v148
	v_fmac_f32_e32 v145, v185, v150
	v_lshlrev_b32_e32 v4, 16, v1
	v_lshlrev_b32_e32 v8, 16, v5
	v_and_b32_e32 v1, 0xffff0000, v1
	v_and_b32_e32 v5, 0xffff0000, v5
	v_fmac_f32_e32 v4, v139, v8
	v_fmac_f32_e32 v1, v145, v5
	v_cvt_pk_bf16_f32 v1, v4, v1
	v_fmac_f32_e32 v147, v189, v152
	v_lshlrev_b32_e32 v4, 16, v2
	v_lshlrev_b32_e32 v5, 16, v6
	v_fmac_f32_e32 v187, v191, v154
	v_fmac_f32_e32 v4, v147, v5
	v_and_b32_e32 v2, 0xffff0000, v2
	v_and_b32_e32 v5, 0xffff0000, v6
	v_fmac_f32_e32 v2, v187, v5
	v_cvt_pk_bf16_f32 v2, v4, v2
	v_fmac_f32_e32 v193, v197, v200
	v_lshlrev_b32_e32 v4, 16, v3
	v_lshlrev_b32_e32 v5, 16, v7
	v_fmac_f32_e32 v195, v199, v202
	v_fmac_f32_e32 v4, v193, v5
	v_and_b32_e32 v3, 0xffff0000, v3
	v_and_b32_e32 v5, 0xffff0000, v7
	v_fmac_f32_e32 v3, v195, v5
	v_cvt_pk_bf16_f32 v3, v4, v3
	v_lshl_add_u64 v[4:5], s[28:29], 0, v[170:171]
	s_and_b64 vcc, exec, s[6:7]
	global_store_dwordx4 v[4:5], v[0:3], off
	s_cbranch_vccnz .LBB0_456
	s_barrier
	s_branch .LBB0_456
